# sgu_spatial: the four Ws-tile row loads per group issued together with the V-tile loads and consumed behind counted vmcnt (was load + full wait x4), on top of v40
# speedup vs baseline: 1.0087x; 1.0074x over previous
; #define LAS __attribute__((address_space(3)))
; __device__ __forceinline__ unsigned pk2(float lo, float hi) { return pg8::cvt_pk_bf16(lo, hi); }
; __device__ __forceinline__ void sgu_spatial(CP pp, LAS unsigned char* lds) {
;     ...
;                 const int cb = tid & 31;
;                 u32x4 raw[8];
; #pragma unroll
;                 for (int it = 0; it < 8; ++it) raw[it] = __builtin_nontemporal_load((const u32x4*)(Zs + (size_t)(r0 + it * 16 + (tid >> 5)) * 4096 + 2048 + 256 * g + 8 * cb));
; #pragma unroll
;                 for (int it = 0; it < 8; ++it) *(LAS u32x4*)(VT + (it * 16 + (tid >> 5)) * 132 + cb * 4) = raw[it];
;             }
; #pragma unroll
;             for (int it = 0; it < 4; ++it) {
;                 const int id = it * NTHR + tid, q = id >> 4, pc = id & 15;
;                 const u32x4 rw = *(const u32x4*)(WsB + (size_t)(g * 128 + q) * 128 + pc * 8);
;                 const f32x4 rs0 = *(const LAS f32x4*)(RS + 8 * pc), rs1 = *(const LAS f32x4*)(RS + 8 * pc + 4), mu0 = *(const LAS f32x4*)(MU + 8 * pc), mu1 = *(const LAS f32x4*)(MU + 8 * pc + 4);
;                 const f32x4 w0 = {bf_lo(rw.x), bf_hi(rw.x), bf_lo(rw.y), bf_hi(rw.y)}, w1 = {bf_lo(rw.z), bf_hi(rw.z), bf_lo(rw.w), bf_hi(rw.w)};
;                 float m2p = (w0[0] + w0[1]) + (w0[2] + w0[3]) + (w1[0] + w1[1]) + (w1[2] + w1[3]);
;                 const f32x4 s0 = w0 * rs0, s1 = w1 * rs1;
;                 u32x4 wp; wp.x = pk2(s0[0], s0[1]); wp.y = pk2(s0[2], s0[3]); wp.z = pk2(s1[0], s1[1]); wp.w = pk2(s1[2], s1[3]);
;                 *(LAS u32x4*)(WST + q * 272 + pc * 16) = wp;
;                 float m1p = (bf_lo(wp.x) * mu0[0] + bf_hi(wp.x) * mu0[1]) + (bf_lo(wp.y) * mu0[2] + bf_hi(wp.y) * mu0[3]) + (bf_lo(wp.z) * mu1[0] + bf_hi(wp.z) * mu1[1]) + (bf_lo(wp.w) * mu1[2] + bf_hi(wp.w) * mu1[3]);
; #pragma unroll
;                 for (int o = 1; o < 16; o <<= 1) { m1p += __shfl_xor(m1p, o); m2p += __shfl_xor(m2p, o); }
;                 if (pc == 0) { M1[q] = m1p; M2[q] = m2p; }
;             }
.LBB0_75:
	v_lshl_add_u64 v[0:1], v[100:101], 0, s[10:11]
	v_lshl_add_u64 v[4:5], v[102:103], 0, s[10:11]
	v_lshl_add_u64 v[8:9], v[104:105], 0, s[10:11]
	v_lshl_add_u64 v[12:13], v[106:107], 0, s[10:11]
	v_lshl_add_u64 v[16:17], v[108:109], 0, s[10:11]
	v_lshl_add_u64 v[20:21], v[110:111], 0, s[10:11]
	v_lshl_add_u64 v[24:25], v[112:113], 0, s[10:11]
	v_lshl_add_u64 v[28:29], v[114:115], 0, s[10:11]
	global_load_dwordx4 v[0:3], v[0:1], off nt
	s_nop 0
	global_load_dwordx4 v[4:7], v[4:5], off nt
	s_nop 0
	global_load_dwordx4 v[8:11], v[8:9], off nt
	s_nop 0
	global_load_dwordx4 v[12:15], v[12:13], off nt
	s_nop 0
	global_load_dwordx4 v[16:19], v[16:17], off nt
	s_nop 0
	global_load_dwordx4 v[20:23], v[20:21], off nt
	s_nop 0
	global_load_dwordx4 v[24:27], v[24:25], off nt
	s_nop 0
	global_load_dwordx4 v[28:31], v[28:29], off nt
	v_lshl_add_u64 v[32:33], v[150:151], 0, v[80:81]
	global_load_dwordx4 v[32:35], v[32:33], off
	v_lshl_add_u64 v[76:77], v[152:153], 0, v[80:81]
	global_load_dwordx4 v[76:79], v[76:77], off
	v_lshl_add_u64 v[72:73], v[154:155], 0, v[80:81]
	global_load_dwordx4 v[72:75], v[72:73], off
	v_lshl_add_u64 v[56:57], v[156:157], 0, v[80:81]
	global_load_dwordx4 v[56:59], v[56:57], off
	s_waitcnt vmcnt(11)
	ds_write_b128 v237, v[0:3]
	s_waitcnt vmcnt(10)
	ds_write_b128 v237, v[4:7] offset:8448
	s_waitcnt vmcnt(9)
	ds_write_b128 v237, v[8:11] offset:16896
	s_waitcnt vmcnt(8)
	ds_write_b128 v237, v[12:15] offset:25344
	s_waitcnt vmcnt(7)
	ds_write_b128 v237, v[16:19] offset:33792
	s_waitcnt vmcnt(6)
	ds_write_b128 v237, v[20:23] offset:42240
	s_waitcnt vmcnt(5)
	ds_write_b128 v237, v[24:27] offset:50688
	s_waitcnt vmcnt(4)
	ds_write_b128 v237, v[28:31] offset:59136
	ds_read_b128 v[0:3], v189
	ds_read_b128 v[4:7], v189 offset:16
	ds_read_b128 v[8:11], v190
	ds_read_b128 v[12:15], v190 offset:16
	s_waitcnt vmcnt(3)
	v_lshlrev_b32_e32 v16, 16, v32
	v_and_b32_e32 v17, 0xffff0000, v32
	v_lshlrev_b32_e32 v18, 16, v33
	v_and_b32_e32 v19, 0xffff0000, v33
	v_lshlrev_b32_e32 v20, 16, v34
	v_and_b32_e32 v21, 0xffff0000, v34
	v_lshlrev_b32_e32 v22, 16, v35
	v_and_b32_e32 v23, 0xffff0000, v35
	s_waitcnt lgkmcnt(3)
	v_pk_mul_f32 v[2:3], v[2:3], v[18:19]
	v_pk_mul_f32 v[0:1], v[0:1], v[16:17]
	v_add_f32_e32 v24, v16, v17
	s_waitcnt lgkmcnt(2)
	v_pk_mul_f32 v[16:17], v[6:7], v[22:23]
	v_pk_mul_f32 v[6:7], v[4:5], v[20:21]
	v_cvt_pk_bf16_f32 v4, v0, v1
	v_cvt_pk_bf16_f32 v5, v2, v3
	v_add_f32_e32 v25, v18, v19
	v_and_b32_e32 v1, 0xffff0000, v4
	v_and_b32_e32 v3, 0xffff0000, v5
	v_cvt_pk_bf16_f32 v6, v6, v7
	v_cvt_pk_bf16_f32 v7, v16, v17
	v_lshlrev_b32_e32 v0, 16, v4
	v_lshlrev_b32_e32 v2, 16, v5
	v_and_b32_e32 v17, 0xffff0000, v6
	s_waitcnt lgkmcnt(1)
	v_mul_f32_e32 v1, v9, v1
	v_mul_f32_e32 v3, v11, v3
	v_lshlrev_b32_e32 v16, 16, v6
	v_and_b32_e32 v19, 0xffff0000, v7
	s_waitcnt lgkmcnt(0)
	v_mul_f32_e32 v9, v13, v17
	v_fmac_f32_e32 v1, v8, v0
	v_fmac_f32_e32 v3, v10, v2
	v_add_f32_e32 v26, v20, v21
	v_add_f32_e32 v24, v24, v25
	v_lshlrev_b32_e32 v18, 16, v7
	v_mul_f32_e32 v11, v15, v19
	v_fmac_f32_e32 v9, v12, v16
	v_add_f32_e32 v0, v1, v3
	v_add_f32_e32 v27, v22, v23
	v_add_f32_e32 v24, v26, v24
	v_fmac_f32_e32 v11, v14, v18
	v_add_f32_e32 v0, v0, v9
	v_add_f32_e32 v24, v27, v24
	v_add_f32_e32 v0, v0, v11
	ds_bpermute_b32 v25, v192, v24
	ds_bpermute_b32 v1, v192, v0
	ds_write_b128 v238, v[4:7]
	s_waitcnt lgkmcnt(2)
	v_add_f32_e32 v2, v24, v25
	s_waitcnt lgkmcnt(1)
	v_add_f32_e32 v0, v0, v1
	ds_bpermute_b32 v3, v193, v2
	ds_bpermute_b32 v1, v193, v0
	s_waitcnt lgkmcnt(1)
	v_add_f32_e32 v2, v2, v3
	s_waitcnt lgkmcnt(0)
	v_add_f32_e32 v0, v0, v1
	ds_bpermute_b32 v3, v194, v2
	ds_bpermute_b32 v8, v194, v0
	s_waitcnt lgkmcnt(1)
	v_add_f32_e32 v1, v2, v3
	s_waitcnt lgkmcnt(0)
	v_add_f32_e32 v0, v0, v8
	ds_bpermute_b32 v2, v195, v0
	ds_bpermute_b32 v3, v195, v1
	s_and_saveexec_b64 s[20:21], s[8:9]
	s_cbranch_execz .LBB0_77
	s_waitcnt lgkmcnt(1)
	v_add_f32_e32 v0, v0, v2
	s_waitcnt lgkmcnt(0)
	v_add_f32_e32 v1, v1, v3
	ds_write_b32 v205, v0
	ds_write_b32 v204, v1
.LBB0_77:
	s_or_b64 exec, exec, s[20:21]
	s_waitcnt vmcnt(2)
	s_waitcnt lgkmcnt(0)
	v_mov_b32_e32 v0, v76
	v_mov_b32_e32 v1, v77
	v_mov_b32_e32 v2, v78
	v_mov_b32_e32 v3, v79
	ds_read_b128 v[4:7], v189
	ds_read_b128 v[8:11], v189 offset:16
	ds_read_b128 v[12:15], v190
	ds_read_b128 v[16:19], v190 offset:16
	s_nop 0
	v_lshlrev_b32_e32 v20, 16, v0
	v_and_b32_e32 v21, 0xffff0000, v0
	v_lshlrev_b32_e32 v0, 16, v1
	v_and_b32_e32 v1, 0xffff0000, v1
	v_lshlrev_b32_e32 v22, 16, v2
	v_and_b32_e32 v23, 0xffff0000, v2
	v_lshlrev_b32_e32 v2, 16, v3
	v_and_b32_e32 v3, 0xffff0000, v3
	v_add_f32_e32 v24, v20, v21
	v_add_f32_e32 v25, v0, v1
	v_add_f32_e32 v26, v22, v23
	v_add_f32_e32 v27, v2, v3
	s_waitcnt lgkmcnt(3)
	v_pk_mul_f32 v[0:1], v[6:7], v[0:1]
	v_pk_mul_f32 v[4:5], v[4:5], v[20:21]
	s_waitcnt lgkmcnt(2)
	v_pk_mul_f32 v[2:3], v[10:11], v[2:3]
	v_pk_mul_f32 v[6:7], v[8:9], v[22:23]
	v_add_f32_e32 v8, v24, v25
	v_cvt_pk_bf16_f32 v4, v4, v5
	v_cvt_pk_bf16_f32 v5, v0, v1
	v_cvt_pk_bf16_f32 v6, v6, v7
	v_cvt_pk_bf16_f32 v7, v2, v3
	v_add_f32_e32 v0, v26, v8
	v_and_b32_e32 v2, 0xffff0000, v4
	v_and_b32_e32 v8, 0xffff0000, v5
	v_lshlrev_b32_e32 v1, 16, v4
	v_lshlrev_b32_e32 v3, 16, v5
	v_and_b32_e32 v10, 0xffff0000, v6
	s_waitcnt lgkmcnt(1)
	v_mul_f32_e32 v2, v13, v2
	v_mul_f32_e32 v8, v15, v8
	v_lshlrev_b32_e32 v9, 16, v6
	v_and_b32_e32 v20, 0xffff0000, v7
	s_waitcnt lgkmcnt(0)
	v_mul_f32_e32 v10, v17, v10
	v_fmac_f32_e32 v2, v12, v1
	v_fmac_f32_e32 v8, v14, v3
	v_lshlrev_b32_e32 v11, 16, v7
	v_mul_f32_e32 v13, v19, v20
	v_fmac_f32_e32 v10, v16, v9
	v_add_f32_e32 v2, v2, v8
	v_fmac_f32_e32 v13, v18, v11
	v_add_f32_e32 v2, v2, v10
	v_add_f32_e32 v0, v27, v0
	v_add_f32_e32 v2, v2, v13
	ds_bpermute_b32 v1, v192, v0
	ds_bpermute_b32 v3, v192, v2
	ds_write_b128 v239, v[4:7]
	s_waitcnt lgkmcnt(2)
	v_add_f32_e32 v0, v0, v1
	s_waitcnt lgkmcnt(1)
	v_add_f32_e32 v2, v2, v3
	ds_bpermute_b32 v1, v193, v0
	ds_bpermute_b32 v3, v193, v2
	s_waitcnt lgkmcnt(1)
	v_add_f32_e32 v0, v0, v1
	s_waitcnt lgkmcnt(0)
	v_add_f32_e32 v2, v2, v3
	ds_bpermute_b32 v1, v194, v0
	ds_bpermute_b32 v3, v194, v2
	s_waitcnt lgkmcnt(1)
	v_add_f32_e32 v1, v0, v1
	s_waitcnt lgkmcnt(0)
	v_add_f32_e32 v0, v2, v3
	ds_bpermute_b32 v2, v195, v0
	ds_bpermute_b32 v3, v195, v1
	s_and_saveexec_b64 s[20:21], s[8:9]
	s_cbranch_execz .LBB0_79
	s_waitcnt lgkmcnt(1)
	v_add_f32_e32 v0, v0, v2
	s_waitcnt lgkmcnt(0)
	v_add_f32_e32 v1, v1, v3
	ds_write_b32 v207, v0
	ds_write_b32 v206, v1
; #define LAS __attribute__((address_space(3)))
; __device__ __forceinline__ unsigned pk2(float lo, float hi) { return pg8::cvt_pk_bf16(lo, hi); }
; __device__ __forceinline__ void sgu_spatial(CP pp, LAS unsigned char* lds) {
;     ...
;             for (int it = 0; it < 4; ++it) {
;                 const int id = it * NTHR + tid, q = id >> 4, pc = id & 15;
;                 const u32x4 rw = *(const u32x4*)(WsB + (size_t)(g * 128 + q) * 128 + pc * 8);
;                 const f32x4 rs0 = *(const LAS f32x4*)(RS + 8 * pc), rs1 = *(const LAS f32x4*)(RS + 8 * pc + 4), mu0 = *(const LAS f32x4*)(MU + 8 * pc), mu1 = *(const LAS f32x4*)(MU + 8 * pc + 4);
;                 const f32x4 w0 = {bf_lo(rw.x), bf_hi(rw.x), bf_lo(rw.y), bf_hi(rw.y)}, w1 = {bf_lo(rw.z), bf_hi(rw.z), bf_lo(rw.w), bf_hi(rw.w)};
;                 float m2p = (w0[0] + w0[1]) + (w0[2] + w0[3]) + (w1[0] + w1[1]) + (w1[2] + w1[3]);
;                 const f32x4 s0 = w0 * rs0, s1 = w1 * rs1;
;                 u32x4 wp; wp.x = pk2(s0[0], s0[1]); wp.y = pk2(s0[2], s0[3]); wp.z = pk2(s1[0], s1[1]); wp.w = pk2(s1[2], s1[3]);
;                 *(LAS u32x4*)(WST + q * 272 + pc * 16) = wp;
;                 float m1p = (bf_lo(wp.x) * mu0[0] + bf_hi(wp.x) * mu0[1]) + (bf_lo(wp.y) * mu0[2] + bf_hi(wp.y) * mu0[3]) + (bf_lo(wp.z) * mu1[0] + bf_hi(wp.z) * mu1[1]) + (bf_lo(wp.w) * mu1[2] + bf_hi(wp.w) * mu1[3]);
; #pragma unroll
;                 for (int o = 1; o < 16; o <<= 1) { m1p += __shfl_xor(m1p, o); m2p += __shfl_xor(m2p, o); }
;                 if (pc == 0) { M1[q] = m1p; M2[q] = m2p; }
;             }
.LBB0_79:
	s_or_b64 exec, exec, s[20:21]
	s_waitcnt vmcnt(1)
	s_waitcnt lgkmcnt(0)
	v_mov_b32_e32 v0, v72
	v_mov_b32_e32 v1, v73
	v_mov_b32_e32 v2, v74
	v_mov_b32_e32 v3, v75
	ds_read_b128 v[4:7], v189
	ds_read_b128 v[8:11], v189 offset:16
	ds_read_b128 v[12:15], v190
	ds_read_b128 v[16:19], v190 offset:16
	s_nop 0
	v_lshlrev_b32_e32 v20, 16, v0
	v_and_b32_e32 v21, 0xffff0000, v0
	v_lshlrev_b32_e32 v0, 16, v1
	v_and_b32_e32 v1, 0xffff0000, v1
	v_lshlrev_b32_e32 v22, 16, v2
	v_and_b32_e32 v23, 0xffff0000, v2
	v_lshlrev_b32_e32 v2, 16, v3
	v_and_b32_e32 v3, 0xffff0000, v3
	v_add_f32_e32 v24, v20, v21
	v_add_f32_e32 v25, v0, v1
	v_add_f32_e32 v26, v22, v23
	v_add_f32_e32 v27, v2, v3
	s_waitcnt lgkmcnt(3)
	v_pk_mul_f32 v[0:1], v[6:7], v[0:1]
	v_pk_mul_f32 v[4:5], v[4:5], v[20:21]
	s_waitcnt lgkmcnt(2)
	v_pk_mul_f32 v[2:3], v[10:11], v[2:3]
	v_pk_mul_f32 v[6:7], v[8:9], v[22:23]
	v_add_f32_e32 v8, v24, v25
	v_cvt_pk_bf16_f32 v4, v4, v5
	v_cvt_pk_bf16_f32 v5, v0, v1
	v_cvt_pk_bf16_f32 v6, v6, v7
	v_cvt_pk_bf16_f32 v7, v2, v3
	v_add_f32_e32 v0, v26, v8
	v_and_b32_e32 v2, 0xffff0000, v4
	v_and_b32_e32 v8, 0xffff0000, v5
	v_lshlrev_b32_e32 v1, 16, v4
	v_lshlrev_b32_e32 v3, 16, v5
	v_and_b32_e32 v10, 0xffff0000, v6
	s_waitcnt lgkmcnt(1)
	v_mul_f32_e32 v2, v13, v2
	v_mul_f32_e32 v8, v15, v8
	v_lshlrev_b32_e32 v9, 16, v6
	v_and_b32_e32 v20, 0xffff0000, v7
	s_waitcnt lgkmcnt(0)
	v_mul_f32_e32 v10, v17, v10
	v_fmac_f32_e32 v2, v12, v1
	v_fmac_f32_e32 v8, v14, v3
	v_lshlrev_b32_e32 v11, 16, v7
	v_mul_f32_e32 v13, v19, v20
	v_fmac_f32_e32 v10, v16, v9
	v_add_f32_e32 v2, v2, v8
	v_fmac_f32_e32 v13, v18, v11
	v_add_f32_e32 v2, v2, v10
	v_add_f32_e32 v0, v27, v0
	v_add_f32_e32 v2, v2, v13
	ds_bpermute_b32 v1, v192, v0
	ds_bpermute_b32 v3, v192, v2
	ds_write_b128 v240, v[4:7]
	s_waitcnt lgkmcnt(2)
	v_add_f32_e32 v0, v0, v1
	s_waitcnt lgkmcnt(1)
	v_add_f32_e32 v2, v2, v3
	ds_bpermute_b32 v1, v193, v0
	ds_bpermute_b32 v3, v193, v2
	s_waitcnt lgkmcnt(1)
	v_add_f32_e32 v0, v0, v1
	s_waitcnt lgkmcnt(0)
	v_add_f32_e32 v2, v2, v3
	ds_bpermute_b32 v1, v194, v0
	ds_bpermute_b32 v3, v194, v2
	s_waitcnt lgkmcnt(1)
	v_add_f32_e32 v1, v0, v1
	s_waitcnt lgkmcnt(0)
	v_add_f32_e32 v0, v2, v3
	ds_bpermute_b32 v2, v195, v0
	ds_bpermute_b32 v3, v195, v1
	s_and_saveexec_b64 s[20:21], s[8:9]
	s_cbranch_execz .LBB0_81
	s_waitcnt lgkmcnt(1)
	v_add_f32_e32 v0, v0, v2
	s_waitcnt lgkmcnt(0)
	v_add_f32_e32 v1, v1, v3
	ds_write_b32 v209, v0
	ds_write_b32 v208, v1
.LBB0_81:
	s_or_b64 exec, exec, s[20:21]
	s_waitcnt vmcnt(0)
	s_waitcnt lgkmcnt(0)
	v_mov_b32_e32 v0, v56
	v_mov_b32_e32 v1, v57
	v_mov_b32_e32 v2, v58
	v_mov_b32_e32 v3, v59
	ds_read_b128 v[4:7], v189
	ds_read_b128 v[8:11], v189 offset:16
	ds_read_b128 v[12:15], v190
	ds_read_b128 v[16:19], v190 offset:16
	s_nop 0
	v_lshlrev_b32_e32 v20, 16, v0
	v_and_b32_e32 v21, 0xffff0000, v0
	v_lshlrev_b32_e32 v0, 16, v1
	v_and_b32_e32 v1, 0xffff0000, v1
	v_lshlrev_b32_e32 v22, 16, v2
	v_and_b32_e32 v23, 0xffff0000, v2
	v_lshlrev_b32_e32 v2, 16, v3
	v_and_b32_e32 v3, 0xffff0000, v3
	v_add_f32_e32 v24, v20, v21
	v_add_f32_e32 v25, v0, v1
	v_add_f32_e32 v26, v22, v23
	v_add_f32_e32 v27, v2, v3
	s_waitcnt lgkmcnt(3)
	v_pk_mul_f32 v[0:1], v[6:7], v[0:1]
	v_pk_mul_f32 v[4:5], v[4:5], v[20:21]
	s_waitcnt lgkmcnt(2)
	v_pk_mul_f32 v[2:3], v[10:11], v[2:3]
	v_pk_mul_f32 v[6:7], v[8:9], v[22:23]
	v_add_f32_e32 v8, v24, v25
	v_cvt_pk_bf16_f32 v4, v4, v5
	v_cvt_pk_bf16_f32 v5, v0, v1
	v_cvt_pk_bf16_f32 v6, v6, v7
	v_cvt_pk_bf16_f32 v7, v2, v3
	v_add_f32_e32 v0, v26, v8
	v_and_b32_e32 v2, 0xffff0000, v4
	v_and_b32_e32 v8, 0xffff0000, v5
	v_lshlrev_b32_e32 v1, 16, v4
	v_lshlrev_b32_e32 v3, 16, v5
	v_and_b32_e32 v10, 0xffff0000, v6
	s_waitcnt lgkmcnt(1)
	v_mul_f32_e32 v2, v13, v2
	v_mul_f32_e32 v8, v15, v8
	v_lshlrev_b32_e32 v9, 16, v6
	v_and_b32_e32 v20, 0xffff0000, v7
	s_waitcnt lgkmcnt(0)
	v_mul_f32_e32 v10, v17, v10
	v_fmac_f32_e32 v2, v12, v1
	v_fmac_f32_e32 v8, v14, v3
	v_lshlrev_b32_e32 v11, 16, v7
	v_mul_f32_e32 v13, v19, v20
	v_fmac_f32_e32 v10, v16, v9
	v_add_f32_e32 v2, v2, v8
	v_fmac_f32_e32 v13, v18, v11
	v_add_f32_e32 v2, v2, v10
	v_add_f32_e32 v0, v27, v0
	v_add_f32_e32 v2, v2, v13
	ds_bpermute_b32 v1, v192, v0
	ds_bpermute_b32 v3, v192, v2
	ds_write_b128 v241, v[4:7]
	s_waitcnt lgkmcnt(2)
	v_add_f32_e32 v0, v0, v1
	s_waitcnt lgkmcnt(1)
	v_add_f32_e32 v2, v2, v3
	ds_bpermute_b32 v1, v193, v0
	ds_bpermute_b32 v3, v193, v2
	s_waitcnt lgkmcnt(1)
	v_add_f32_e32 v0, v0, v1
	s_waitcnt lgkmcnt(0)
	v_add_f32_e32 v2, v2, v3
	ds_bpermute_b32 v1, v194, v0
	ds_bpermute_b32 v3, v194, v2
	s_waitcnt lgkmcnt(1)
	v_add_f32_e32 v1, v0, v1
	s_waitcnt lgkmcnt(0)
	v_add_f32_e32 v0, v2, v3
	ds_bpermute_b32 v2, v195, v0
	ds_bpermute_b32 v3, v195, v1
	s_and_saveexec_b64 s[20:21], s[8:9]
	s_cbranch_execz .LBB0_74
	s_waitcnt lgkmcnt(1)
	v_add_f32_e32 v0, v0, v2
	s_waitcnt lgkmcnt(0)
	v_add_f32_e32 v1, v1, v3
	ds_write_b32 v211, v0
	ds_write_b32 v210, v1
	s_branch .LBB0_74
